# strategy 2 residual: lru_pre second staging loop (2 serialized loads for tid<128) issued together; rest = v15
# baseline (speedup 1.0000x reference)
; __device__ __forceinline__ void lru_pre(const Params& p, unsigned char* lds) {
;     ...
;     for (int e = tid; e < 640; e += 512) { const int j = e >> 7, c = e & 127; cw[e] = j < 4 ? p.conv_w[j * 1024 + c0 + c] : p.conv_b[c0 + c]; }
.LBB0_370:
	v_cmp_gt_u32_e32 vcc, 0x80, v162
	s_and_saveexec_b64 s[2:3], vcc
	global_load_dword v7, v[4:5], off
	s_mov_b64 exec, s[2:3]
	v_and_or_b32 v2, v58, s10, v0
	v_lshlrev_b32_e32 v2, 2, v2
	v_lshl_add_u64 v[8:9], s[50:51], 0, v[2:3]
	global_load_dword v2, v[8:9], off
	s_waitcnt vmcnt(0)
	ds_write_b32 v1, v2
	s_and_saveexec_b64 s[2:3], vcc
	ds_write_b32 v1, v7 offset:2048
	s_mov_b64 exec, s[2:3]
